# lever 7 (DPP instead of LDS round trips): NSA compressed pass-2 importance group sums via v_mov_b32_dpp quad_perm instead of 32 ds_bpermute + waits per tile, on v_m25
# baseline (speedup 1.0000x reference)
.LBB0_244:
	s_waitcnt vmcnt(7)
	v_mfma_f32_32x32x16_bf16 v[18:33], v[114:117], v[90:93], 0
	s_mov_b32 s0, s15
	s_add_i32 s15, s15, 1
	s_cmp_lt_u32 s15, s12
	s_waitcnt vmcnt(1)
	v_mov_b64_e32 v[192:193], v[120:121]
	s_cselect_b32 s94, s15, s0
	v_mov_b64_e32 v[190:191], v[118:119]
	v_mov_b64_e32 v[120:121], v[104:105]
	v_mfma_f32_32x32x16_bf16 v[18:33], v[94:97], v[130:133], v[18:33]
	s_lshl_b64 s[0:1], s[94:95], 13
	v_mov_b64_e32 v[118:119], v[102:103]
	v_add_co_u32_e64 v102, s[40:41], s33, v182
	s_add_u32 s0, s42, s0
	v_mov_b64_e32 v[218:219], v[112:113]
	v_addc_co_u32_e64 v103, s[40:41], 0, v183, s[40:41]
	v_mfma_f32_32x32x16_bf16 v[18:33], v[98:101], v[134:137], v[18:33]
	s_addc_u32 s1, s43, s1
	v_mov_b64_e32 v[216:217], v[110:111]
	global_load_dwordx4 v[166:169], v[182:183], off
	global_load_dwordx4 v[162:165], v[182:183], off offset:1024
	global_load_dwordx4 v[158:161], v[182:183], off offset:2048
	global_load_dwordx4 v[142:145], v[182:183], off offset:3072
	global_load_dwordx4 v[150:153], v[102:103], off
	global_load_dwordx4 v[154:157], v[102:103], off offset:1024
	global_load_dwordx4 v[146:149], v[102:103], off offset:2048
	global_load_dwordx4 v[126:129], v[102:103], off offset:3072
	s_waitcnt vmcnt(8)
	v_mov_b64_e32 v[206:207], v[124:125]
	v_mov_b64_e32 v[204:205], v[122:123]
	v_or_b32_e32 v189, 47, v170
	v_mfma_f32_32x32x16_bf16 v[2:17], v[106:109], v[90:93], 0
	global_load_dwordx4 v[114:117], v0, s[0:1]
	global_load_dwordx4 v[94:97], v0, s[0:1] offset:1024
	global_load_dwordx4 v[98:101], v0, s[0:1] offset:2048
	global_load_dwordx4 v[102:105], v0, s[0:1] offset:3072
	global_load_dwordx4 v[106:109], v172, s[0:1]
	global_load_dwordx4 v[110:113], v174, s[0:1]
	v_or_b32_e32 v196, 31, v170
	v_cmp_le_i32_e64 s[40:41], v189, v171
	v_add_u32_e32 v189, 63, v170
	v_mfma_f32_32x32x16_bf16 v[18:33], v[118:121], v[138:141], v[18:33]
	global_load_dwordx4 v[118:121], v176, s[0:1]
	global_load_dwordx4 v[122:125], v178, s[0:1]
	v_mfma_f32_32x32x16_bf16 v[2:17], v[216:219], v[130:133], v[2:17]
	s_nop 8
	v_fmamk_f32 v18, v18, 0x3e38aa3b, v173
	v_fmamk_f32 v19, v19, 0x3e38aa3b, v173
	v_exp_f32_e32 v18, v18
	v_exp_f32_e32 v19, v19
	v_fmamk_f32 v21, v21, 0x3e38aa3b, v173
	v_pk_mul_f32 v[194:195], v[180:181], v[18:19]
	v_fmamk_f32 v19, v20, 0x3e38aa3b, v173
	v_exp_f32_e32 v19, v19
	v_mfma_f32_32x32x16_bf16 v[2:17], v[190:193], v[134:137], v[2:17]
	v_exp_f32_e32 v190, v21
	v_cndmask_b32_e64 v18, 0, v195, s[40:41]
	v_cmp_le_i32_e64 s[40:41], v196, v200
	v_mul_f32_e32 v19, v180, v19
	s_nop 0
	v_cndmask_b32_e64 v20, 0, v194, s[40:41]
	v_cmp_le_i32_e64 s[40:41], v189, v200
	v_mul_f32_e32 v189, v180, v190
	v_mfma_f32_32x32x16_bf16 v[2:17], v[204:207], v[138:141], v[2:17]
	v_cndmask_b32_e64 v21, 0, v19, s[40:41]
	v_add_u32_e32 v19, 0x4f, v170
	v_cmp_le_i32_e64 s[40:41], v19, v200
	v_add_f32_e32 v19, v20, v18
	s_nop 0
	v_cndmask_b32_e64 v189, 0, v189, s[40:41]
	v_add_f32_e32 v190, v21, v189
	v_add_f32_e32 v19, v19, v190
	s_nop 1
	v_mov_b32_dpp v190, v19 quad_perm:[1,0,3,2] row_mask:0xf bank_mask:0xf
	v_mov_b32_dpp v191, v189 quad_perm:[1,0,3,2] row_mask:0xf bank_mask:0xf
	v_add_f32_e32 v193, v19, v190
	v_add_f32_e32 v191, v189, v191
	s_nop 1
	v_mov_b32_dpp v197, v193 quad_perm:[2,3,0,1] row_mask:0xf bank_mask:0xf
	v_mov_b32_dpp v192, v191 quad_perm:[2,3,0,1] row_mask:0xf bank_mask:0xf
	v_mov_b32_e32 v19, v170
	v_add_u32_e32 v190, s13, v188
	s_and_saveexec_b64 s[0:1], vcc
	s_cbranch_execz .LBB0_247
	v_add_f32_e32 v193, v193, v197
	ds_add_f32 v179, v193
	v_cmp_gt_u32_e64 s[40:41], s17, v190
	s_and_b64 exec, exec, s[40:41]
	s_cbranch_execz .LBB0_247
	v_add_f32_e32 v191, v191, v192
	ds_add_f32 v179, v191 offset:4
.LBB0_247:
	s_or_b64 exec, exec, s[0:1]
	v_fmamk_f32 v22, v22, 0x3e38aa3b, v173
	v_fmamk_f32 v23, v23, 0x3e38aa3b, v173
	v_exp_f32_e32 v22, v22
	v_exp_f32_e32 v23, v23
	v_fmamk_f32 v25, v25, 0x3e38aa3b, v173
	v_or_b32_e32 v191, 0xaf, v19
	v_exp_f32_e32 v25, v25
	v_pk_mul_f32 v[192:193], v[180:181], v[22:23]
	v_fmamk_f32 v23, v24, 0x3e38aa3b, v173
	v_exp_f32_e32 v24, v23
	v_or_b32_e32 v194, 0x9f, v170
	v_cmp_le_i32_e64 s[40:41], v191, v171
	v_add_u32_e32 v191, 0xbf, v170
	v_mul_f32_e32 v24, v180, v24
	v_cndmask_b32_e64 v22, 0, v193, s[40:41]
	v_cmp_le_i32_e64 s[40:41], v194, v200
	v_mul_f32_e32 v25, v180, v25
	s_nop 0
	v_cndmask_b32_e64 v23, 0, v192, s[40:41]
	v_cmp_le_i32_e64 s[40:41], v191, v200
	v_add_u32_e32 v191, 0xcf, v170
	s_nop 0
	v_cndmask_b32_e64 v24, 0, v24, s[40:41]
	v_cmp_le_i32_e64 s[40:41], v191, v200
	v_add_f32_e32 v191, v23, v22
	s_nop 0
	v_cndmask_b32_e64 v25, 0, v25, s[40:41]
	v_add_f32_e32 v192, v24, v25
	v_add_f32_e32 v191, v191, v192
	s_nop 1
	v_mov_b32_dpp v192, v191 quad_perm:[1,0,3,2] row_mask:0xf bank_mask:0xf
	v_mov_b32_dpp v194, v25 quad_perm:[1,0,3,2] row_mask:0xf bank_mask:0xf
	v_add_f32_e32 v193, v191, v192
	v_add_f32_e32 v191, v25, v194
	s_nop 1
	v_mov_b32_dpp v197, v193 quad_perm:[2,3,0,1] row_mask:0xf bank_mask:0xf
	v_mov_b32_dpp v192, v191 quad_perm:[2,3,0,1] row_mask:0xf bank_mask:0xf
	s_and_saveexec_b64 s[0:1], vcc
	s_cbranch_execz .LBB0_250
	v_add_f32_e32 v193, v193, v197
	ds_add_f32 v179, v193 offset:8
	v_add_u32_e32 v193, 2, v190
	v_cmp_gt_u32_e64 s[40:41], s17, v193
	s_and_b64 exec, exec, s[40:41]
	s_cbranch_execz .LBB0_250
	v_add_f32_e32 v191, v191, v192
	ds_add_f32 v179, v191 offset:12
.LBB0_250:
	s_or_b64 exec, exec, s[0:1]
	v_fmamk_f32 v26, v26, 0x3e38aa3b, v173
	v_fmamk_f32 v27, v27, 0x3e38aa3b, v173
	v_exp_f32_e32 v26, v26
	v_exp_f32_e32 v27, v27
	v_fmamk_f32 v29, v29, 0x3e38aa3b, v173
	v_or_b32_e32 v191, 0x12f, v19
	v_exp_f32_e32 v29, v29
	v_pk_mul_f32 v[192:193], v[180:181], v[26:27]
	v_fmamk_f32 v27, v28, 0x3e38aa3b, v173
	v_exp_f32_e32 v28, v27
	v_or_b32_e32 v194, 0x11f, v170
	v_cmp_le_i32_e64 s[40:41], v191, v171
	v_add_u32_e32 v191, 0x13f, v170
	v_mul_f32_e32 v28, v180, v28
	v_cndmask_b32_e64 v26, 0, v193, s[40:41]
	v_cmp_le_i32_e64 s[40:41], v194, v200
	v_mul_f32_e32 v29, v180, v29
	s_nop 0
	v_cndmask_b32_e64 v27, 0, v192, s[40:41]
	v_cmp_le_i32_e64 s[40:41], v191, v200
	v_add_u32_e32 v191, 0x14f, v170
	s_nop 0
	v_cndmask_b32_e64 v28, 0, v28, s[40:41]
	v_cmp_le_i32_e64 s[40:41], v191, v200
	v_add_f32_e32 v191, v27, v26
	s_nop 0
	v_cndmask_b32_e64 v29, 0, v29, s[40:41]
	v_add_f32_e32 v192, v28, v29
	v_add_f32_e32 v191, v191, v192
	s_nop 1
	v_mov_b32_dpp v192, v191 quad_perm:[1,0,3,2] row_mask:0xf bank_mask:0xf
	v_mov_b32_dpp v194, v29 quad_perm:[1,0,3,2] row_mask:0xf bank_mask:0xf
	v_add_f32_e32 v193, v191, v192
	v_add_f32_e32 v191, v29, v194
	s_nop 1
	v_mov_b32_dpp v197, v193 quad_perm:[2,3,0,1] row_mask:0xf bank_mask:0xf
	v_mov_b32_dpp v192, v191 quad_perm:[2,3,0,1] row_mask:0xf bank_mask:0xf
	s_and_saveexec_b64 s[0:1], vcc
	s_cbranch_execz .LBB0_253
	v_add_f32_e32 v193, v193, v197
	ds_add_f32 v179, v193 offset:16
	v_add_u32_e32 v193, 4, v190
	v_cmp_gt_u32_e64 s[40:41], s17, v193
	s_and_b64 exec, exec, s[40:41]
	s_cbranch_execz .LBB0_253
	v_add_f32_e32 v191, v191, v192
	ds_add_f32 v179, v191 offset:20
.LBB0_253:
	s_or_b64 exec, exec, s[0:1]
	v_fmamk_f32 v30, v30, 0x3e38aa3b, v173
	v_fmamk_f32 v31, v31, 0x3e38aa3b, v173
	v_exp_f32_e32 v30, v30
	v_exp_f32_e32 v31, v31
	v_fmamk_f32 v33, v33, 0x3e38aa3b, v173
	v_or_b32_e32 v191, 0x1af, v19
	v_exp_f32_e32 v33, v33
	v_pk_mul_f32 v[192:193], v[180:181], v[30:31]
	v_fmamk_f32 v31, v32, 0x3e38aa3b, v173
	v_exp_f32_e32 v32, v31
	v_or_b32_e32 v194, 0x19f, v170
	v_cmp_le_i32_e64 s[40:41], v191, v171
	v_add_u32_e32 v191, 0x1bf, v170
	v_mul_f32_e32 v32, v180, v32
	v_cndmask_b32_e64 v30, 0, v193, s[40:41]
	v_cmp_le_i32_e64 s[40:41], v194, v200
	v_mul_f32_e32 v33, v180, v33
	s_nop 0
	v_cndmask_b32_e64 v31, 0, v192, s[40:41]
	v_cmp_le_i32_e64 s[40:41], v191, v200
	v_add_u32_e32 v191, 0x1cf, v170
	s_nop 0
	v_cndmask_b32_e64 v32, 0, v32, s[40:41]
	v_cmp_le_i32_e64 s[40:41], v191, v200
	v_add_f32_e32 v191, v31, v30
	s_nop 0
	v_cndmask_b32_e64 v33, 0, v33, s[40:41]
	v_add_f32_e32 v192, v32, v33
	v_add_f32_e32 v191, v191, v192
	s_nop 1
	v_mov_b32_dpp v192, v191 quad_perm:[1,0,3,2] row_mask:0xf bank_mask:0xf
	v_mov_b32_dpp v194, v33 quad_perm:[1,0,3,2] row_mask:0xf bank_mask:0xf
	v_add_f32_e32 v193, v191, v192
	v_add_f32_e32 v191, v33, v194
	s_nop 1
	v_mov_b32_dpp v197, v193 quad_perm:[2,3,0,1] row_mask:0xf bank_mask:0xf
	v_mov_b32_dpp v192, v191 quad_perm:[2,3,0,1] row_mask:0xf bank_mask:0xf
	s_and_saveexec_b64 s[0:1], vcc
	s_cbranch_execz .LBB0_256
	v_add_f32_e32 v193, v193, v197
	ds_add_f32 v179, v193 offset:24
	v_add_u32_e32 v193, 6, v190
	v_cmp_gt_u32_e64 s[40:41], s17, v193
	s_and_b64 exec, exec, s[40:41]
	s_cbranch_execz .LBB0_256
	v_add_f32_e32 v191, v191, v192
	ds_add_f32 v179, v191 offset:28
.LBB0_256:
	s_or_b64 exec, exec, s[0:1]
	v_fmamk_f32 v2, v2, 0x3e38aa3b, v173
	v_fmamk_f32 v3, v3, 0x3e38aa3b, v173
	v_exp_f32_e32 v2, v2
	v_exp_f32_e32 v3, v3
	v_fmamk_f32 v5, v5, 0x3e38aa3b, v173
	v_or_b32_e32 v191, 0x22f, v19
	v_exp_f32_e32 v5, v5
	v_pk_mul_f32 v[192:193], v[180:181], v[2:3]
	v_fmamk_f32 v3, v4, 0x3e38aa3b, v173
	v_exp_f32_e32 v4, v3
	v_or_b32_e32 v194, 0x21f, v170
	v_cmp_le_i32_e64 s[40:41], v191, v171
	v_add_u32_e32 v191, 0x23f, v170
	v_mul_f32_e32 v4, v180, v4
	v_cndmask_b32_e64 v2, 0, v193, s[40:41]
	v_cmp_le_i32_e64 s[40:41], v194, v200
	v_mul_f32_e32 v5, v180, v5
	s_nop 0
	v_cndmask_b32_e64 v3, 0, v192, s[40:41]
	v_cmp_le_i32_e64 s[40:41], v191, v200
	v_add_u32_e32 v191, 0x24f, v170
	s_nop 0
	v_cndmask_b32_e64 v4, 0, v4, s[40:41]
	v_cmp_le_i32_e64 s[40:41], v191, v200
	v_add_f32_e32 v191, v3, v2
	s_nop 0
	v_cndmask_b32_e64 v5, 0, v5, s[40:41]
	v_add_f32_e32 v192, v4, v5
	v_add_f32_e32 v191, v191, v192
	s_nop 1
	v_mov_b32_dpp v192, v191 quad_perm:[1,0,3,2] row_mask:0xf bank_mask:0xf
	v_mov_b32_dpp v194, v5 quad_perm:[1,0,3,2] row_mask:0xf bank_mask:0xf
	v_add_f32_e32 v193, v191, v192
	v_add_f32_e32 v191, v5, v194
	s_nop 1
	v_mov_b32_dpp v197, v193 quad_perm:[2,3,0,1] row_mask:0xf bank_mask:0xf
	v_mov_b32_dpp v192, v191 quad_perm:[2,3,0,1] row_mask:0xf bank_mask:0xf
	s_and_saveexec_b64 s[0:1], vcc
	s_cbranch_execz .LBB0_259
	v_add_f32_e32 v193, v193, v197
	ds_add_f32 v179, v193 offset:32
	v_add_u32_e32 v193, 8, v190
	v_cmp_gt_u32_e64 s[40:41], s17, v193
	s_and_b64 exec, exec, s[40:41]
	s_cbranch_execz .LBB0_259
	v_add_f32_e32 v191, v191, v192
	ds_add_f32 v179, v191 offset:36
.LBB0_259:
	s_or_b64 exec, exec, s[0:1]
	v_fmamk_f32 v6, v6, 0x3e38aa3b, v173
	v_fmamk_f32 v7, v7, 0x3e38aa3b, v173
	v_exp_f32_e32 v6, v6
	v_exp_f32_e32 v7, v7
	v_fmamk_f32 v9, v9, 0x3e38aa3b, v173
	v_or_b32_e32 v191, 0x2af, v19
	v_exp_f32_e32 v9, v9
	v_pk_mul_f32 v[192:193], v[180:181], v[6:7]
	v_fmamk_f32 v7, v8, 0x3e38aa3b, v173
	v_exp_f32_e32 v8, v7
	v_or_b32_e32 v194, 0x29f, v170
	v_cmp_le_i32_e64 s[40:41], v191, v171
	v_add_u32_e32 v191, 0x2bf, v170
	v_mul_f32_e32 v8, v180, v8
	v_cndmask_b32_e64 v6, 0, v193, s[40:41]
	v_cmp_le_i32_e64 s[40:41], v194, v200
	v_mul_f32_e32 v9, v180, v9
	s_nop 0
	v_cndmask_b32_e64 v7, 0, v192, s[40:41]
	v_cmp_le_i32_e64 s[40:41], v191, v200
	v_add_u32_e32 v191, 0x2cf, v170
	s_nop 0
	v_cndmask_b32_e64 v8, 0, v8, s[40:41]
	v_cmp_le_i32_e64 s[40:41], v191, v200
	v_add_f32_e32 v191, v7, v6
	s_nop 0
	v_cndmask_b32_e64 v9, 0, v9, s[40:41]
	v_add_f32_e32 v192, v8, v9
	v_add_f32_e32 v191, v191, v192
	s_nop 1
	v_mov_b32_dpp v192, v191 quad_perm:[1,0,3,2] row_mask:0xf bank_mask:0xf
	v_mov_b32_dpp v194, v9 quad_perm:[1,0,3,2] row_mask:0xf bank_mask:0xf
	v_add_f32_e32 v193, v191, v192
	v_add_f32_e32 v191, v9, v194
	s_nop 1
	v_mov_b32_dpp v197, v193 quad_perm:[2,3,0,1] row_mask:0xf bank_mask:0xf
	v_mov_b32_dpp v192, v191 quad_perm:[2,3,0,1] row_mask:0xf bank_mask:0xf
	s_and_saveexec_b64 s[0:1], vcc
	s_cbranch_execz .LBB0_262
	v_add_f32_e32 v193, v193, v197
	ds_add_f32 v179, v193 offset:40
	v_add_u32_e32 v193, 10, v190
	v_cmp_gt_u32_e64 s[40:41], s17, v193
	s_and_b64 exec, exec, s[40:41]
	s_cbranch_execz .LBB0_262
	v_add_f32_e32 v191, v191, v192
	ds_add_f32 v179, v191 offset:44
.LBB0_262:
	s_or_b64 exec, exec, s[0:1]
	v_fmamk_f32 v10, v10, 0x3e38aa3b, v173
	v_fmamk_f32 v11, v11, 0x3e38aa3b, v173
	v_exp_f32_e32 v10, v10
	v_exp_f32_e32 v11, v11
	v_fmamk_f32 v13, v13, 0x3e38aa3b, v173
	v_or_b32_e32 v191, 0x32f, v19
	v_exp_f32_e32 v13, v13
	v_pk_mul_f32 v[192:193], v[180:181], v[10:11]
	v_fmamk_f32 v11, v12, 0x3e38aa3b, v173
	v_exp_f32_e32 v12, v11
	v_or_b32_e32 v194, 0x31f, v170
	v_cmp_le_i32_e64 s[40:41], v191, v171
	v_add_u32_e32 v191, 0x33f, v170
	v_mul_f32_e32 v12, v180, v12
	v_cndmask_b32_e64 v10, 0, v193, s[40:41]
	v_cmp_le_i32_e64 s[40:41], v194, v200
	v_mul_f32_e32 v13, v180, v13
	s_nop 0
	v_cndmask_b32_e64 v11, 0, v192, s[40:41]
	v_cmp_le_i32_e64 s[40:41], v191, v200
	v_add_u32_e32 v191, 0x34f, v170
	s_nop 0
	v_cndmask_b32_e64 v12, 0, v12, s[40:41]
	v_cmp_le_i32_e64 s[40:41], v191, v200
	v_add_f32_e32 v191, v11, v10
	s_nop 0
	v_cndmask_b32_e64 v13, 0, v13, s[40:41]
	v_add_f32_e32 v192, v12, v13
	v_add_f32_e32 v191, v191, v192
	s_nop 1
	v_mov_b32_dpp v192, v191 quad_perm:[1,0,3,2] row_mask:0xf bank_mask:0xf
	v_mov_b32_dpp v194, v13 quad_perm:[1,0,3,2] row_mask:0xf bank_mask:0xf
	v_add_f32_e32 v193, v191, v192
	v_add_f32_e32 v191, v13, v194
	s_nop 1
	v_mov_b32_dpp v197, v193 quad_perm:[2,3,0,1] row_mask:0xf bank_mask:0xf
	v_mov_b32_dpp v192, v191 quad_perm:[2,3,0,1] row_mask:0xf bank_mask:0xf
	s_and_saveexec_b64 s[0:1], vcc
	s_cbranch_execz .LBB0_265
	v_add_f32_e32 v193, v193, v197
	ds_add_f32 v179, v193 offset:48
	v_add_u32_e32 v193, 12, v190
	v_cmp_gt_u32_e64 s[40:41], s17, v193
	s_and_b64 exec, exec, s[40:41]
	s_cbranch_execz .LBB0_265
	v_add_f32_e32 v191, v191, v192
	ds_add_f32 v179, v191 offset:52
.LBB0_265:
	s_or_b64 exec, exec, s[0:1]
	v_fmamk_f32 v14, v14, 0x3e38aa3b, v173
	v_fmamk_f32 v15, v15, 0x3e38aa3b, v173
	v_exp_f32_e32 v14, v14
	v_exp_f32_e32 v15, v15
	v_fmamk_f32 v17, v17, 0x3e38aa3b, v173
	v_or_b32_e32 v19, 0x3af, v19
	v_exp_f32_e32 v17, v17
	v_pk_mul_f32 v[192:193], v[180:181], v[14:15]
	v_fmamk_f32 v15, v16, 0x3e38aa3b, v173
	v_exp_f32_e32 v16, v15
	v_or_b32_e32 v191, 0x39f, v170
	v_cmp_le_i32_e64 s[40:41], v19, v171
	v_add_u32_e32 v19, 0x3bf, v170
	v_mul_f32_e32 v16, v180, v16
	v_cndmask_b32_e64 v14, 0, v193, s[40:41]
	v_cmp_le_i32_e64 s[40:41], v191, v200
	v_mul_f32_e32 v17, v180, v17
	s_nop 0
	v_cndmask_b32_e64 v15, 0, v192, s[40:41]
	v_cmp_le_i32_e64 s[40:41], v19, v200
	v_add_u32_e32 v19, 0x3cf, v170
	s_nop 0
	v_cndmask_b32_e64 v16, 0, v16, s[40:41]
	v_cmp_le_i32_e64 s[40:41], v19, v200
	v_add_f32_e32 v19, v15, v14
	s_nop 0
	v_cndmask_b32_e64 v17, 0, v17, s[40:41]
	v_add_f32_e32 v191, v16, v17
	v_add_f32_e32 v19, v19, v191
	s_nop 1
	v_mov_b32_dpp v191, v19 quad_perm:[1,0,3,2] row_mask:0xf bank_mask:0xf
	v_mov_b32_dpp v193, v17 quad_perm:[1,0,3,2] row_mask:0xf bank_mask:0xf
	v_add_f32_e32 v192, v19, v191
	v_add_f32_e32 v19, v17, v193
	s_nop 1
	v_mov_b32_dpp v193, v192 quad_perm:[2,3,0,1] row_mask:0xf bank_mask:0xf
	v_mov_b32_dpp v191, v19 quad_perm:[2,3,0,1] row_mask:0xf bank_mask:0xf
	s_and_saveexec_b64 s[0:1], vcc
	s_cbranch_execz .LBB0_243
	v_add_f32_e32 v192, v192, v193
	ds_add_f32 v179, v192 offset:56
	v_add_u32_e32 v190, 14, v190
	v_cmp_gt_u32_e64 s[40:41], s17, v190
	s_and_b64 exec, exec, s[40:41]
	s_cbranch_execz .LBB0_243
	v_add_f32_e32 v19, v19, v191
	ds_add_f32 v179, v19 offset:60
	s_branch .LBB0_243
